# write-through stores for next-chunk weight conversion and attention outputs
# speedup vs baseline: 1.0102x; 1.0030x over previous
.LBB0_1215:
	s_waitcnt lgkmcnt(1)
	v_cvt_pk_bf16_f32 v52, v52, v53
	v_cvt_pk_bf16_f32 v53, v54, v55
	s_waitcnt lgkmcnt(0)
	v_cvt_pk_bf16_f32 v54, v48, v49
	v_cvt_pk_bf16_f32 v55, v50, v51
	global_store_dwordx4 v[142:143], v[52:55], off sc1
	ds_read_b128 v[52:55], v57 offset:2112
	ds_read_b128 v[48:51], v57 offset:2128
	s_and_b64 vcc, exec, s[44:45]
	s_cbranch_vccnz .LBB0_1217
	ds_read_b32 v58, v56 offset:16
	s_waitcnt vmcnt(1)
	v_lshlrev_b32_e32 v60, 16, v96
	v_and_b32_e32 v61, 0xffff0000, v96
	s_waitcnt lgkmcnt(0)
	v_pk_fma_f32 v[52:53], v[58:59], v[60:61], v[52:53] op_sel_hi:[0,1,1]
	v_lshlrev_b32_e32 v60, 16, v97
	v_and_b32_e32 v61, 0xffff0000, v97
	v_pk_fma_f32 v[54:55], v[58:59], v[60:61], v[54:55] op_sel_hi:[0,1,1]
	v_lshlrev_b32_e32 v60, 16, v98
	v_and_b32_e32 v61, 0xffff0000, v98
	v_pk_fma_f32 v[48:49], v[58:59], v[60:61], v[48:49] op_sel_hi:[0,1,1]
	v_lshlrev_b32_e32 v60, 16, v99
	v_and_b32_e32 v61, 0xffff0000, v99
	v_pk_fma_f32 v[50:51], v[58:59], v[60:61], v[50:51] op_sel_hi:[0,1,1]

.LBB0_1219:
	s_waitcnt lgkmcnt(1)
	v_cvt_pk_bf16_f32 v52, v52, v53
	v_cvt_pk_bf16_f32 v53, v54, v55
	s_waitcnt lgkmcnt(0)
	v_cvt_pk_bf16_f32 v54, v48, v49
	v_cvt_pk_bf16_f32 v55, v50, v51
	v_lshl_add_u64 v[48:49], s[0:1], 1, v[142:143]
	global_store_dwordx4 v[48:49], v[52:55], off sc1
	ds_read_b128 v[52:55], v57 offset:4224
	ds_read_b128 v[48:51], v57 offset:4240
	s_and_b64 vcc, exec, s[44:45]
	s_cbranch_vccnz .LBB0_1221
	ds_read_b32 v58, v56 offset:32
	s_waitcnt vmcnt(2)
	v_lshlrev_b32_e32 v60, 16, v88
	v_and_b32_e32 v61, 0xffff0000, v88
	s_waitcnt lgkmcnt(0)
	v_pk_fma_f32 v[52:53], v[58:59], v[60:61], v[52:53] op_sel_hi:[0,1,1]
	v_lshlrev_b32_e32 v60, 16, v89
	v_and_b32_e32 v61, 0xffff0000, v89
	v_pk_fma_f32 v[54:55], v[58:59], v[60:61], v[54:55] op_sel_hi:[0,1,1]
	v_lshlrev_b32_e32 v60, 16, v90
	v_and_b32_e32 v61, 0xffff0000, v90
	v_pk_fma_f32 v[48:49], v[58:59], v[60:61], v[48:49] op_sel_hi:[0,1,1]
	v_lshlrev_b32_e32 v60, 16, v91
	v_and_b32_e32 v61, 0xffff0000, v91
	v_pk_fma_f32 v[50:51], v[58:59], v[60:61], v[50:51] op_sel_hi:[0,1,1]

.LBB0_1223:
	s_waitcnt lgkmcnt(1)
	v_cvt_pk_bf16_f32 v52, v52, v53
	v_cvt_pk_bf16_f32 v53, v54, v55
	s_waitcnt lgkmcnt(0)
	v_cvt_pk_bf16_f32 v54, v48, v49
	v_cvt_pk_bf16_f32 v55, v50, v51
	v_lshl_add_u64 v[48:49], s[82:83], 1, v[142:143]
	global_store_dwordx4 v[48:49], v[52:55], off sc1
	ds_read_b128 v[52:55], v57 offset:6336
	ds_read_b128 v[48:51], v57 offset:6352
	s_and_b64 vcc, exec, s[44:45]
	s_cbranch_vccnz .LBB0_1225
	ds_read_b32 v58, v56 offset:48
	s_waitcnt vmcnt(3)
	v_lshlrev_b32_e32 v60, 16, v80
	v_and_b32_e32 v61, 0xffff0000, v80
	s_waitcnt lgkmcnt(0)
	v_pk_fma_f32 v[52:53], v[58:59], v[60:61], v[52:53] op_sel_hi:[0,1,1]
	v_lshlrev_b32_e32 v60, 16, v81
	v_and_b32_e32 v61, 0xffff0000, v81
	v_pk_fma_f32 v[54:55], v[58:59], v[60:61], v[54:55] op_sel_hi:[0,1,1]
	v_lshlrev_b32_e32 v60, 16, v82
	v_and_b32_e32 v61, 0xffff0000, v82
	v_pk_fma_f32 v[48:49], v[58:59], v[60:61], v[48:49] op_sel_hi:[0,1,1]
	v_lshlrev_b32_e32 v60, 16, v83
	v_and_b32_e32 v61, 0xffff0000, v83
	v_pk_fma_f32 v[50:51], v[58:59], v[60:61], v[50:51] op_sel_hi:[0,1,1]

.LBB0_1227:
	s_waitcnt lgkmcnt(1)
	v_cvt_pk_bf16_f32 v52, v52, v53
	v_cvt_pk_bf16_f32 v53, v54, v55
	s_waitcnt lgkmcnt(0)
	v_cvt_pk_bf16_f32 v54, v48, v49
	v_cvt_pk_bf16_f32 v55, v50, v51
	v_lshl_add_u64 v[48:49], s[84:85], 1, v[142:143]
	global_store_dwordx4 v[48:49], v[52:55], off sc1
	ds_read_b128 v[52:55], v57 offset:8448
	ds_read_b128 v[48:51], v57 offset:8464
	s_and_b64 vcc, exec, s[44:45]
	s_cbranch_vccnz .LBB0_1229
	ds_read_b32 v58, v56 offset:64
	s_waitcnt vmcnt(4)
	v_lshlrev_b32_e32 v60, 16, v76
	v_and_b32_e32 v61, 0xffff0000, v76
	s_waitcnt lgkmcnt(0)
	v_pk_fma_f32 v[52:53], v[58:59], v[60:61], v[52:53] op_sel_hi:[0,1,1]
	v_lshlrev_b32_e32 v60, 16, v77
	v_and_b32_e32 v61, 0xffff0000, v77
	v_pk_fma_f32 v[54:55], v[58:59], v[60:61], v[54:55] op_sel_hi:[0,1,1]
	v_lshlrev_b32_e32 v60, 16, v78
	v_and_b32_e32 v61, 0xffff0000, v78
	v_pk_fma_f32 v[48:49], v[58:59], v[60:61], v[48:49] op_sel_hi:[0,1,1]
	v_lshlrev_b32_e32 v60, 16, v79
	v_and_b32_e32 v61, 0xffff0000, v79
	v_pk_fma_f32 v[50:51], v[58:59], v[60:61], v[50:51] op_sel_hi:[0,1,1]

.LBB0_1231:
	s_waitcnt lgkmcnt(1)
	v_cvt_pk_bf16_f32 v52, v52, v53
	v_cvt_pk_bf16_f32 v53, v54, v55
	s_waitcnt lgkmcnt(0)
	v_cvt_pk_bf16_f32 v54, v48, v49
	v_cvt_pk_bf16_f32 v55, v50, v51
	v_lshl_add_u64 v[48:49], s[86:87], 1, v[142:143]
	global_store_dwordx4 v[48:49], v[52:55], off sc1
	ds_read_b128 v[52:55], v57 offset:10560
	ds_read_b128 v[48:51], v57 offset:10576
	s_and_b64 vcc, exec, s[44:45]
	s_cbranch_vccnz .LBB0_1233
	ds_read_b32 v58, v56 offset:80
	s_waitcnt vmcnt(5)
	v_lshlrev_b32_e32 v60, 16, v72
	v_and_b32_e32 v61, 0xffff0000, v72
	s_waitcnt lgkmcnt(0)
	v_pk_fma_f32 v[52:53], v[58:59], v[60:61], v[52:53] op_sel_hi:[0,1,1]
	v_lshlrev_b32_e32 v60, 16, v73
	v_and_b32_e32 v61, 0xffff0000, v73
	v_pk_fma_f32 v[54:55], v[58:59], v[60:61], v[54:55] op_sel_hi:[0,1,1]
	v_lshlrev_b32_e32 v60, 16, v74
	v_and_b32_e32 v61, 0xffff0000, v74
	v_pk_fma_f32 v[48:49], v[58:59], v[60:61], v[48:49] op_sel_hi:[0,1,1]
	v_lshlrev_b32_e32 v60, 16, v75
	v_and_b32_e32 v61, 0xffff0000, v75
	v_pk_fma_f32 v[50:51], v[58:59], v[60:61], v[50:51] op_sel_hi:[0,1,1]

.LBB0_1235:
	s_waitcnt lgkmcnt(1)
	v_cvt_pk_bf16_f32 v52, v52, v53
	v_cvt_pk_bf16_f32 v53, v54, v55
	s_waitcnt lgkmcnt(0)
	v_cvt_pk_bf16_f32 v54, v48, v49
	v_cvt_pk_bf16_f32 v55, v50, v51
	v_lshl_add_u64 v[48:49], s[88:89], 1, v[142:143]
	global_store_dwordx4 v[48:49], v[52:55], off sc1
	ds_read_b128 v[52:55], v57 offset:12672
	ds_read_b128 v[48:51], v57 offset:12688
	s_and_b64 vcc, exec, s[44:45]
	s_cbranch_vccnz .LBB0_1237
	ds_read_b32 v58, v56 offset:96
	s_waitcnt vmcnt(6)
	v_lshlrev_b32_e32 v60, 16, v68
	v_and_b32_e32 v61, 0xffff0000, v68
	s_waitcnt lgkmcnt(0)
	v_pk_fma_f32 v[52:53], v[58:59], v[60:61], v[52:53] op_sel_hi:[0,1,1]
	v_lshlrev_b32_e32 v60, 16, v69
	v_and_b32_e32 v61, 0xffff0000, v69
	v_pk_fma_f32 v[54:55], v[58:59], v[60:61], v[54:55] op_sel_hi:[0,1,1]
	v_lshlrev_b32_e32 v60, 16, v70
	v_and_b32_e32 v61, 0xffff0000, v70
	v_pk_fma_f32 v[48:49], v[58:59], v[60:61], v[48:49] op_sel_hi:[0,1,1]
	v_lshlrev_b32_e32 v60, 16, v71
	v_and_b32_e32 v61, 0xffff0000, v71
	v_pk_fma_f32 v[50:51], v[58:59], v[60:61], v[50:51] op_sel_hi:[0,1,1]

.LBB0_1239:
	s_waitcnt lgkmcnt(1)
	v_cvt_pk_bf16_f32 v52, v52, v53
	v_cvt_pk_bf16_f32 v53, v54, v55
	s_waitcnt lgkmcnt(0)
	v_cvt_pk_bf16_f32 v54, v48, v49
	v_cvt_pk_bf16_f32 v55, v50, v51
	v_lshl_add_u64 v[48:49], s[90:91], 1, v[142:143]
	global_store_dwordx4 v[48:49], v[52:55], off sc1
	ds_read_b128 v[52:55], v57 offset:14784
	ds_read_b128 v[48:51], v57 offset:14800
	s_and_b64 vcc, exec, s[44:45]
	s_cbranch_vccnz .LBB0_1241
	ds_read_b32 v56, v56 offset:112
	s_waitcnt vmcnt(7)
	v_lshlrev_b32_e32 v58, 16, v64
	v_and_b32_e32 v59, 0xffff0000, v64
	s_waitcnt lgkmcnt(0)
	v_pk_fma_f32 v[52:53], v[56:57], v[58:59], v[52:53] op_sel_hi:[0,1,1]
	v_lshlrev_b32_e32 v58, 16, v65
	v_and_b32_e32 v59, 0xffff0000, v65
	v_pk_fma_f32 v[54:55], v[56:57], v[58:59], v[54:55] op_sel_hi:[0,1,1]
	v_lshlrev_b32_e32 v58, 16, v66
	v_and_b32_e32 v59, 0xffff0000, v66
	v_pk_fma_f32 v[48:49], v[56:57], v[58:59], v[48:49] op_sel_hi:[0,1,1]
	v_lshlrev_b32_e32 v58, 16, v67
	v_and_b32_e32 v59, 0xffff0000, v67
	v_pk_fma_f32 v[50:51], v[56:57], v[58:59], v[50:51] op_sel_hi:[0,1,1]

.LBB0_1243:
	s_waitcnt lgkmcnt(1)
	v_cvt_pk_bf16_f32 v52, v52, v53
	v_cvt_pk_bf16_f32 v53, v54, v55
	s_waitcnt lgkmcnt(0)
	v_cvt_pk_bf16_f32 v54, v48, v49
	v_cvt_pk_bf16_f32 v55, v50, v51
	v_lshl_add_u64 v[48:49], s[92:93], 1, v[142:143]
	s_mov_b64 s[12:13], -1
	s_and_b64 vcc, exec, s[94:95]
	global_store_dwordx4 v[48:49], v[52:55], off sc1
	s_barrier
	s_cbranch_vccz .LBB0_1130
	s_waitcnt vmcnt(16)
	ds_write_b128 v151, v[0:3]
	ds_write_b128 v151, v[8:11] offset:8192
	ds_write_b128 v151, v[4:7] offset:16384
	ds_write_b128 v151, v[12:15] offset:24576
	s_waitcnt vmcnt(15)
	ds_write_b128 v151, v[16:19] offset:32768
	s_waitcnt vmcnt(14)
	ds_write_b128 v151, v[20:23] offset:40960
	s_waitcnt vmcnt(13)
	ds_write_b128 v151, v[24:27] offset:49152
	s_waitcnt vmcnt(12)
	ds_write_b128 v151, v[28:31] offset:57344
	s_waitcnt vmcnt(11)
	ds_write_b128 v153, v[32:35]
	s_waitcnt vmcnt(10)
	ds_write_b128 v154, v[36:39]
	s_waitcnt vmcnt(9)
	ds_write_b128 v155, v[40:43]
	s_waitcnt vmcnt(8)
	ds_write_b128 v156, v[44:47]
	s_mov_b64 s[12:13], 0
	s_branch .LBB0_1130

.LBB0_1247:
	s_load_dwordx2 s[10:11], s[8:9], 0x58
	s_and_b32 s0, s5, 0xffffffc0
	v_or_b32_e32 v2, s0, v5
	v_ashrrev_i32_e32 v3, 31, v2
	s_and_b32 s7, s4, 0x3e0
	v_lshlrev_b64 v[2:3], 12, v[2:3]
	s_waitcnt lgkmcnt(0)
	v_lshl_add_u64 v[2:3], s[10:11], 0, v[2:3]
	s_lshl_b32 s56, s7, 2
	v_lshl_add_u64 v[2:3], v[2:3], 0, s[56:57]
	v_lshl_add_u64 v[2:3], v[2:3], 0, v[138:139]
	s_movk_i32 s1, 0x2000
	v_add_co_u32_e32 v12, vcc, s1, v2
	s_movk_i32 s1, 0x4000
	s_nop 0
	v_addc_co_u32_e32 v13, vcc, 0, v3, vcc
	global_load_dword v20, v[2:3], off
	global_load_dword v21, v[12:13], off
	v_add_co_u32_e32 v12, vcc, s1, v2
	s_movk_i32 s1, 0x6000
	s_nop 0
	v_addc_co_u32_e32 v13, vcc, 0, v3, vcc
	global_load_dword v22, v[12:13], off
	v_add_co_u32_e32 v12, vcc, s1, v2
	s_mov_b32 s1, 0x18000
	s_nop 0
	v_addc_co_u32_e32 v13, vcc, 0, v3, vcc
	global_load_dword v23, v[12:13], off
	v_add_co_u32_e32 v12, vcc, s19, v2
	s_add_i32 s6, s6, s39
	s_nop 0
	v_addc_co_u32_e32 v13, vcc, 0, v3, vcc
	v_add_co_u32_e32 v14, vcc, s20, v2
	global_load_dword v12, v[12:13], off
	s_nop 0
	v_addc_co_u32_e32 v15, vcc, 0, v3, vcc
	global_load_dword v13, v[14:15], off
	v_add_co_u32_e32 v14, vcc, s21, v2
	s_add_i32 s5, s5, s12
	s_nop 0
	v_addc_co_u32_e32 v15, vcc, 0, v3, vcc
	v_add_co_u32_e32 v16, vcc, s22, v2
	global_load_dword v15, v[14:15], off
	s_nop 0
	v_addc_co_u32_e32 v17, vcc, 0, v3, vcc
	global_load_dword v18, v[16:17], off
	v_add_co_u32_e32 v16, vcc, s63, v2
	s_add_i32 s4, s4, s13
	s_nop 0
	v_addc_co_u32_e32 v17, vcc, 0, v3, vcc
	global_load_dword v14, v[16:17], off
	v_add_co_u32_e32 v16, vcc, s14, v2
	s_nop 1
	v_addc_co_u32_e32 v17, vcc, 0, v3, vcc
	v_add_co_u32_e32 v24, vcc, s15, v2
	global_load_dword v16, v[16:17], off
	s_nop 0
	v_addc_co_u32_e32 v25, vcc, 0, v3, vcc
	global_load_dword v17, v[24:25], off
	v_add_co_u32_e32 v24, vcc, s18, v2
	s_nop 1
	v_addc_co_u32_e32 v25, vcc, 0, v3, vcc
	global_load_dword v19, v[24:25], off
	v_add_co_u32_e32 v24, vcc, s1, v2
	s_mov_b32 s1, 0x1a000
	s_nop 0
	v_addc_co_u32_e32 v25, vcc, 0, v3, vcc
	v_add_co_u32_e32 v26, vcc, s1, v2
	s_mov_b32 s1, 0x1c000
	s_nop 0
	v_addc_co_u32_e32 v27, vcc, 0, v3, vcc
	global_load_dword v24, v[24:25], off
	s_nop 0
	global_load_dword v25, v[26:27], off
	v_add_co_u32_e32 v26, vcc, s1, v2
	s_mov_b32 s1, 0x1e000
	s_nop 0
	v_addc_co_u32_e32 v27, vcc, 0, v3, vcc
	v_add_co_u32_e32 v28, vcc, s1, v2
	s_mov_b32 s1, 0x22000
	s_nop 0
	v_addc_co_u32_e32 v29, vcc, 0, v3, vcc
	v_add_co_u32_e32 v30, vcc, s53, v2
	global_load_dword v26, v[26:27], off
	s_nop 0
	v_addc_co_u32_e32 v31, vcc, 0, v3, vcc
	global_load_dword v28, v[28:29], off
	s_nop 0
	global_load_dword v27, v[30:31], off
	v_add_co_u32_e32 v30, vcc, s1, v2
	s_mov_b32 s1, 0x24000
	s_nop 0
	v_addc_co_u32_e32 v31, vcc, 0, v3, vcc
	global_load_dword v29, v[30:31], off
	v_add_co_u32_e32 v30, vcc, s1, v2
	s_mov_b32 s1, 0x26000
	s_nop 0
	v_addc_co_u32_e32 v31, vcc, 0, v3, vcc
	global_load_dword v32, v[30:31], off
	v_add_co_u32_e32 v30, vcc, s1, v2
	s_mov_b32 s1, 0x28000
	s_nop 0
	v_addc_co_u32_e32 v31, vcc, 0, v3, vcc
	global_load_dword v33, v[30:31], off
	v_add_co_u32_e32 v30, vcc, s1, v2
	s_mov_b32 s1, 0x2a000
	s_nop 0
	v_addc_co_u32_e32 v31, vcc, 0, v3, vcc
	global_load_dword v34, v[30:31], off
	v_add_co_u32_e32 v30, vcc, s1, v2
	s_mov_b32 s1, 0x2c000
	s_nop 0
	v_addc_co_u32_e32 v31, vcc, 0, v3, vcc
	global_load_dword v35, v[30:31], off
	v_add_co_u32_e32 v30, vcc, s1, v2
	s_mov_b32 s1, 0x2e000
	s_nop 0
	v_addc_co_u32_e32 v31, vcc, 0, v3, vcc
	global_load_dword v36, v[30:31], off
	v_add_co_u32_e32 v30, vcc, s1, v2
	s_mov_b32 s1, 0x32000
	s_nop 0
	v_addc_co_u32_e32 v31, vcc, 0, v3, vcc
	global_load_dword v37, v[30:31], off
	v_add_co_u32_e32 v30, vcc, s23, v2
	s_nop 1
	v_addc_co_u32_e32 v31, vcc, 0, v3, vcc
	global_load_dword v38, v[30:31], off
	v_add_co_u32_e32 v30, vcc, s1, v2
	s_mov_b32 s1, 0x34000
	s_nop 0
	v_addc_co_u32_e32 v31, vcc, 0, v3, vcc
	global_load_dword v39, v[30:31], off
	v_add_co_u32_e32 v30, vcc, s1, v2
	s_mov_b32 s1, 0x36000
	s_nop 0
	v_addc_co_u32_e32 v31, vcc, 0, v3, vcc
	global_load_dword v40, v[30:31], off
	v_add_co_u32_e32 v30, vcc, s1, v2
	s_mov_b32 s1, 0x38000
	s_nop 0
	v_addc_co_u32_e32 v31, vcc, 0, v3, vcc
	global_load_dword v41, v[30:31], off
	v_add_co_u32_e32 v30, vcc, s1, v2
	s_mov_b32 s1, 0x3a000
	s_nop 0
	v_addc_co_u32_e32 v31, vcc, 0, v3, vcc
	global_load_dword v42, v[30:31], off
	v_add_co_u32_e32 v30, vcc, s1, v2
	s_mov_b32 s1, 0x3c000
	s_nop 0
	v_addc_co_u32_e32 v31, vcc, 0, v3, vcc
	global_load_dword v43, v[30:31], off
	v_add_co_u32_e32 v30, vcc, s1, v2
	s_mov_b32 s1, 0x3e000
	s_nop 0
	v_addc_co_u32_e32 v31, vcc, 0, v3, vcc
	v_add_co_u32_e32 v2, vcc, s1, v2
	global_load_dword v30, v[30:31], off
	s_nop 0
	v_addc_co_u32_e32 v3, vcc, 0, v3, vcc
	global_load_dword v2, v[2:3], off
	v_add_u32_e32 v3, 0x400, v11
	s_waitcnt vmcnt(30)
	ds_write2_b32 v11, v20, v21 offset1:66
	s_waitcnt vmcnt(28)
	ds_write2_b32 v11, v22, v23 offset0:132 offset1:198
	s_waitcnt vmcnt(26)
	ds_write2_b32 v3, v12, v13 offset0:8 offset1:74
	s_waitcnt vmcnt(24)
	ds_write2_b32 v3, v15, v18 offset0:140 offset1:206
	v_add_u32_e32 v3, 0x800, v11
	s_waitcnt vmcnt(22)
	ds_write2_b32 v3, v14, v16 offset0:16 offset1:82
	s_waitcnt vmcnt(20)
	ds_write2_b32 v3, v17, v19 offset0:148 offset1:214
	v_add_u32_e32 v3, 0xc00, v11
	s_waitcnt vmcnt(18)
	ds_write2_b32 v3, v24, v25 offset0:24 offset1:90
	s_waitcnt vmcnt(16)
	ds_write2_b32 v3, v26, v28 offset0:156 offset1:222
	v_add_u32_e32 v3, 0x1000, v11
	s_waitcnt vmcnt(14)
	ds_write2_b32 v3, v27, v29 offset0:32 offset1:98
	s_waitcnt vmcnt(12)
	ds_write2_b32 v3, v32, v33 offset0:164 offset1:230
	v_add_u32_e32 v3, 0x1400, v11
	s_waitcnt vmcnt(10)
	ds_write2_b32 v3, v34, v35 offset0:40 offset1:106
	s_waitcnt vmcnt(8)
	ds_write2_b32 v3, v36, v37 offset0:172 offset1:238
	v_add_u32_e32 v3, 0x1800, v11
	s_waitcnt vmcnt(6)
	ds_write2_b32 v3, v38, v39 offset0:48 offset1:114
	s_waitcnt vmcnt(4)
	ds_write2_b32 v3, v40, v41 offset0:180 offset1:246
	v_add_u32_e32 v3, 0x1c00, v11
	s_waitcnt vmcnt(2)
	ds_write2_b32 v3, v42, v43 offset0:56 offset1:122
	s_waitcnt vmcnt(0)
	ds_write2_b32 v3, v30, v2 offset0:188 offset1:254
	s_waitcnt lgkmcnt(0)
	ds_read2_b32 v[16:17], v7 offset0:33 offset1:41
	ds_read2_b32 v[18:19], v7 offset1:8
	ds_read2_b32 v[20:21], v7 offset0:66 offset1:74
	ds_read2_b32 v[22:23], v7 offset0:99 offset1:107
	ds_read2_b32 v[24:25], v7 offset0:132 offset1:140
	ds_read2_b32 v[26:27], v7 offset0:165 offset1:173
	ds_read2_b32 v[28:29], v7 offset0:198 offset1:206
	ds_read2_b32 v[30:31], v7 offset0:231 offset1:239
	s_ashr_i32 s1, s0, 31
	s_waitcnt lgkmcnt(6)
	v_cvt_pk_bf16_f32 v12, v18, v16
	v_or_b32_e32 v16, s7, v6
	v_lshl_add_u64 v[2:3], s[0:1], 1, v[0:1]
	v_lshlrev_b32_e32 v32, 12, v16
	v_mov_b32_e32 v33, v139
	s_waitcnt lgkmcnt(4)
	v_cvt_pk_bf16_f32 v13, v20, v22
	s_waitcnt lgkmcnt(2)
	v_cvt_pk_bf16_f32 v14, v24, v26
	s_waitcnt lgkmcnt(0)
	v_cvt_pk_bf16_f32 v15, v28, v30
	v_lshl_add_u64 v[32:33], v[2:3], 0, v[32:33]
	v_or_b32_e32 v16, s7, v8
	global_store_dwordx4 v[32:33], v[12:15], off sc1
	v_lshlrev_b32_e32 v16, 12, v16
	v_mov_b32_e32 v33, v139
	v_cvt_pk_bf16_f32 v12, v19, v17
	v_mov_b32_e32 v17, v139
	v_cvt_pk_bf16_f32 v13, v21, v23
	v_cvt_pk_bf16_f32 v14, v25, v27
	v_cvt_pk_bf16_f32 v15, v29, v31
	v_lshl_add_u64 v[16:17], v[2:3], 0, v[16:17]
	global_store_dwordx4 v[16:17], v[12:15], off sc1
	ds_read2_b32 v[16:17], v7 offset0:49 offset1:57
	ds_read2_b32 v[18:19], v7 offset0:16 offset1:24
	ds_read2_b32 v[20:21], v7 offset0:82 offset1:90
	ds_read2_b32 v[22:23], v7 offset0:115 offset1:123
	ds_read2_b32 v[24:25], v7 offset0:148 offset1:156
	ds_read2_b32 v[26:27], v7 offset0:181 offset1:189
	ds_read2_b32 v[28:29], v7 offset0:214 offset1:222
	ds_read2_b32 v[30:31], v7 offset0:247 offset1:255
	s_cmpk_lt_i32 s6, 0x400
	s_waitcnt lgkmcnt(6)
	v_cvt_pk_bf16_f32 v12, v18, v16
	v_or_b32_e32 v16, s7, v9
	v_lshlrev_b32_e32 v32, 12, v16
	s_waitcnt lgkmcnt(4)
	v_cvt_pk_bf16_f32 v13, v20, v22
	s_waitcnt lgkmcnt(2)
	v_cvt_pk_bf16_f32 v14, v24, v26
	s_waitcnt lgkmcnt(0)
	v_cvt_pk_bf16_f32 v15, v28, v30
	v_lshl_add_u64 v[32:33], v[2:3], 0, v[32:33]
	v_or_b32_e32 v16, s7, v10
	global_store_dwordx4 v[32:33], v[12:15], off sc1
	v_lshlrev_b32_e32 v16, 12, v16
	s_nop 0
	v_cvt_pk_bf16_f32 v12, v19, v17
	v_mov_b32_e32 v17, v139
	v_cvt_pk_bf16_f32 v13, v21, v23
	v_cvt_pk_bf16_f32 v14, v25, v27
	v_cvt_pk_bf16_f32 v15, v29, v31
	v_lshl_add_u64 v[2:3], v[2:3], 0, v[16:17]
	global_store_dwordx4 v[2:3], v[12:15], off sc1
	s_waitcnt lgkmcnt(0)
	s_cbranch_scc1 .LBB0_1247

.LBB0_1252:
	s_waitcnt vmcnt(0)
	v_mul_f32_e32 v6, v40, v9
	ds_write2_b32 v11, v8, v6 offset0:140 offset1:206
	s_waitcnt lgkmcnt(0)
	ds_read2_b32 v[12:13], v56 offset0:33 offset1:41
	ds_read2_b32 v[14:15], v56 offset1:8
	ds_read2_b32 v[16:17], v56 offset0:66 offset1:74
	ds_read2_b32 v[18:19], v56 offset0:99 offset1:107
	ds_read2_b32 v[20:21], v56 offset0:132 offset1:140
	ds_read2_b32 v[22:23], v56 offset0:165 offset1:173
	ds_read2_b32 v[24:25], v56 offset0:198 offset1:206
	ds_read2_b32 v[26:27], v56 offset0:231 offset1:239
	v_or_b32_e32 v28, s12, v55
	v_ashrrev_i32_e32 v29, 31, v28
	v_lshl_add_u64 v[10:11], s[14:15], 1, v[4:5]
	v_lshlrev_b64 v[28:29], 11, v[28:29]
	s_waitcnt lgkmcnt(6)
	v_cvt_pk_bf16_f32 v6, v14, v12
	s_waitcnt lgkmcnt(4)
	v_cvt_pk_bf16_f32 v7, v16, v18
	s_waitcnt lgkmcnt(2)
	v_cvt_pk_bf16_f32 v8, v20, v22
	s_waitcnt lgkmcnt(0)
	v_cvt_pk_bf16_f32 v9, v24, v26
	v_lshl_add_u64 v[28:29], v[10:11], 0, v[28:29]
	v_or_b32_e32 v12, s12, v57
	global_store_dwordx4 v[28:29], v[6:9], off sc1
	v_or_b32_e32 v28, s12, v58
	v_ashrrev_i32_e32 v29, 31, v28
	v_cvt_pk_bf16_f32 v6, v15, v13
	v_ashrrev_i32_e32 v13, 31, v12
	v_lshlrev_b64 v[12:13], 11, v[12:13]
	v_cvt_pk_bf16_f32 v7, v17, v19
	v_cvt_pk_bf16_f32 v8, v21, v23
	v_cvt_pk_bf16_f32 v9, v25, v27
	v_lshl_add_u64 v[12:13], v[10:11], 0, v[12:13]
	global_store_dwordx4 v[12:13], v[6:9], off sc1
	ds_read2_b32 v[12:13], v56 offset0:49 offset1:57
	ds_read2_b32 v[14:15], v56 offset0:16 offset1:24
	ds_read2_b32 v[16:17], v56 offset0:82 offset1:90
	ds_read2_b32 v[18:19], v56 offset0:115 offset1:123
	ds_read2_b32 v[20:21], v56 offset0:148 offset1:156
	ds_read2_b32 v[22:23], v56 offset0:181 offset1:189
	ds_read2_b32 v[24:25], v56 offset0:214 offset1:222
	ds_read2_b32 v[26:27], v56 offset0:247 offset1:255
	v_lshlrev_b64 v[28:29], 11, v[28:29]
	s_waitcnt lgkmcnt(6)
	v_cvt_pk_bf16_f32 v6, v14, v12
	s_waitcnt lgkmcnt(4)
	v_cvt_pk_bf16_f32 v7, v16, v18
	s_waitcnt lgkmcnt(2)
	v_cvt_pk_bf16_f32 v8, v20, v22
	s_waitcnt lgkmcnt(0)
	v_cvt_pk_bf16_f32 v9, v24, v26
	v_lshl_add_u64 v[28:29], v[10:11], 0, v[28:29]
	v_or_b32_e32 v12, s12, v59
	global_store_dwordx4 v[28:29], v[6:9], off sc1
	s_nop 1
	v_cvt_pk_bf16_f32 v6, v15, v13
	v_ashrrev_i32_e32 v13, 31, v12
	v_lshlrev_b64 v[12:13], 11, v[12:13]
	v_cvt_pk_bf16_f32 v7, v17, v19
	v_cvt_pk_bf16_f32 v8, v21, v23
	v_cvt_pk_bf16_f32 v9, v25, v27
	v_lshl_add_u64 v[10:11], v[10:11], 0, v[12:13]
	global_store_dwordx4 v[10:11], v[6:9], off sc1
	s_waitcnt lgkmcnt(0)

.LBB0_1280:
	s_waitcnt vmcnt(0)
	v_mul_f32_e32 v8, v8, v9
	ds_write2_b32 v6, v7, v8 offset0:140 offset1:206
	s_waitcnt lgkmcnt(0)
	ds_read2_b32 v[12:13], v56 offset0:33 offset1:41
	ds_read2_b32 v[14:15], v56 offset1:8
	ds_read2_b32 v[16:17], v56 offset0:66 offset1:74
	ds_read2_b32 v[18:19], v56 offset0:99 offset1:107
	ds_read2_b32 v[20:21], v56 offset0:132 offset1:140
	ds_read2_b32 v[22:23], v56 offset0:165 offset1:173
	ds_read2_b32 v[24:25], v56 offset0:198 offset1:206
	ds_read2_b32 v[26:27], v56 offset0:231 offset1:239
	s_add_i32 s18, s18, s24
	v_or_b32_e32 v28, s18, v55
	v_ashrrev_i32_e32 v29, 31, v28
	v_lshl_add_u64 v[10:11], s[14:15], 1, v[4:5]
	v_lshlrev_b64 v[28:29], 11, v[28:29]
	s_waitcnt lgkmcnt(6)
	v_cvt_pk_bf16_f32 v6, v14, v12
	s_waitcnt lgkmcnt(4)
	v_cvt_pk_bf16_f32 v7, v16, v18
	s_waitcnt lgkmcnt(2)
	v_cvt_pk_bf16_f32 v8, v20, v22
	s_waitcnt lgkmcnt(0)
	v_cvt_pk_bf16_f32 v9, v24, v26
	v_lshl_add_u64 v[28:29], v[10:11], 0, v[28:29]
	v_or_b32_e32 v12, s18, v57
	global_store_dwordx4 v[28:29], v[6:9], off sc1
	v_or_b32_e32 v28, s18, v58
	v_ashrrev_i32_e32 v29, 31, v28
	v_cvt_pk_bf16_f32 v6, v15, v13
	v_ashrrev_i32_e32 v13, 31, v12
	v_lshlrev_b64 v[12:13], 11, v[12:13]
	v_cvt_pk_bf16_f32 v7, v17, v19
	v_cvt_pk_bf16_f32 v8, v21, v23
	v_cvt_pk_bf16_f32 v9, v25, v27
	v_lshl_add_u64 v[12:13], v[10:11], 0, v[12:13]
	global_store_dwordx4 v[12:13], v[6:9], off sc1
	ds_read2_b32 v[12:13], v56 offset0:49 offset1:57
	ds_read2_b32 v[14:15], v56 offset0:16 offset1:24
	ds_read2_b32 v[16:17], v56 offset0:82 offset1:90
	ds_read2_b32 v[18:19], v56 offset0:115 offset1:123
	ds_read2_b32 v[20:21], v56 offset0:148 offset1:156
	ds_read2_b32 v[22:23], v56 offset0:181 offset1:189
	ds_read2_b32 v[24:25], v56 offset0:214 offset1:222
	ds_read2_b32 v[26:27], v56 offset0:247 offset1:255
	v_lshlrev_b64 v[28:29], 11, v[28:29]
	s_waitcnt lgkmcnt(6)
	v_cvt_pk_bf16_f32 v6, v14, v12
	s_waitcnt lgkmcnt(4)
	v_cvt_pk_bf16_f32 v7, v16, v18
	s_waitcnt lgkmcnt(2)
	v_cvt_pk_bf16_f32 v8, v20, v22
	s_waitcnt lgkmcnt(0)
	v_cvt_pk_bf16_f32 v9, v24, v26
	v_lshl_add_u64 v[28:29], v[10:11], 0, v[28:29]
	v_or_b32_e32 v12, s18, v59
	global_store_dwordx4 v[28:29], v[6:9], off sc1
	s_mov_b64 s[14:15], 0
	s_nop 0
	v_cvt_pk_bf16_f32 v6, v15, v13
	v_ashrrev_i32_e32 v13, 31, v12
	v_lshlrev_b64 v[12:13], 11, v[12:13]
	v_cvt_pk_bf16_f32 v7, v17, v19
	v_cvt_pk_bf16_f32 v8, v21, v23
	v_cvt_pk_bf16_f32 v9, v25, v27
	v_lshl_add_u64 v[10:11], v[10:11], 0, v[12:13]
	global_store_dwordx4 v[10:11], v[6:9], off sc1
	s_waitcnt lgkmcnt(0)

.LBB0_1308:
	s_waitcnt vmcnt(0)
	v_mul_f32_e32 v8, v8, v14
	ds_write2_b32 v9, v13, v8 offset0:140 offset1:206
	s_waitcnt lgkmcnt(0)
	ds_read2_b32 v[14:15], v56 offset0:33 offset1:41
	ds_read2_b32 v[16:17], v56 offset1:8
	ds_read2_b32 v[18:19], v56 offset0:66 offset1:74
	ds_read2_b32 v[20:21], v56 offset0:99 offset1:107
	ds_read2_b32 v[22:23], v56 offset0:132 offset1:140
	ds_read2_b32 v[24:25], v56 offset0:165 offset1:173
	ds_read2_b32 v[26:27], v56 offset0:198 offset1:206
	ds_read2_b32 v[28:29], v56 offset0:231 offset1:239
	s_add_i32 s12, s20, s28
	v_or_b32_e32 v30, s12, v55
	v_ashrrev_i32_e32 v31, 31, v30
	v_lshl_add_u64 v[12:13], s[18:19], 1, v[4:5]
	v_lshlrev_b64 v[30:31], 11, v[30:31]
	s_waitcnt lgkmcnt(6)
	v_cvt_pk_bf16_f32 v8, v16, v14
	s_waitcnt lgkmcnt(4)
	v_cvt_pk_bf16_f32 v9, v18, v20
	s_waitcnt lgkmcnt(2)
	v_cvt_pk_bf16_f32 v10, v22, v24
	s_waitcnt lgkmcnt(0)
	v_cvt_pk_bf16_f32 v11, v26, v28
	v_lshl_add_u64 v[30:31], v[12:13], 0, v[30:31]
	v_or_b32_e32 v14, s12, v57
	global_store_dwordx4 v[30:31], v[8:11], off sc1
	v_or_b32_e32 v30, s12, v58
	v_ashrrev_i32_e32 v31, 31, v30
	v_cvt_pk_bf16_f32 v8, v17, v15
	v_ashrrev_i32_e32 v15, 31, v14
	v_lshlrev_b64 v[14:15], 11, v[14:15]
	v_cvt_pk_bf16_f32 v9, v19, v21
	v_cvt_pk_bf16_f32 v10, v23, v25
	v_cvt_pk_bf16_f32 v11, v27, v29
	v_lshl_add_u64 v[14:15], v[12:13], 0, v[14:15]
	global_store_dwordx4 v[14:15], v[8:11], off sc1
	ds_read2_b32 v[14:15], v56 offset0:49 offset1:57
	ds_read2_b32 v[16:17], v56 offset0:16 offset1:24
	ds_read2_b32 v[18:19], v56 offset0:82 offset1:90
	ds_read2_b32 v[20:21], v56 offset0:115 offset1:123
	ds_read2_b32 v[22:23], v56 offset0:148 offset1:156
	ds_read2_b32 v[24:25], v56 offset0:181 offset1:189
	ds_read2_b32 v[26:27], v56 offset0:214 offset1:222
	ds_read2_b32 v[28:29], v56 offset0:247 offset1:255
	v_lshlrev_b64 v[30:31], 11, v[30:31]
	s_waitcnt lgkmcnt(6)
	v_cvt_pk_bf16_f32 v8, v16, v14
	s_waitcnt lgkmcnt(4)
	v_cvt_pk_bf16_f32 v9, v18, v20
	s_waitcnt lgkmcnt(2)
	v_cvt_pk_bf16_f32 v10, v22, v24
	s_waitcnt lgkmcnt(0)
	v_cvt_pk_bf16_f32 v11, v26, v28
	v_lshl_add_u64 v[30:31], v[12:13], 0, v[30:31]
	v_or_b32_e32 v14, s12, v59
	global_store_dwordx4 v[30:31], v[8:11], off sc1
	s_mov_b64 s[12:13], 0
	s_nop 0
	v_cvt_pk_bf16_f32 v8, v17, v15
	v_ashrrev_i32_e32 v15, 31, v14
	v_lshlrev_b64 v[14:15], 11, v[14:15]
	v_cvt_pk_bf16_f32 v9, v19, v21
	v_cvt_pk_bf16_f32 v10, v23, v25
	v_cvt_pk_bf16_f32 v11, v27, v29
	v_lshl_add_u64 v[12:13], v[12:13], 0, v[14:15]
	global_store_dwordx4 v[12:13], v[8:11], off sc1
	s_waitcnt lgkmcnt(0)

.LBB0_1334:
	s_waitcnt vmcnt(0)
	v_mul_f32_e32 v8, v8, v9
	ds_write2_b32 v6, v7, v8 offset0:140 offset1:206
	s_waitcnt lgkmcnt(0)
	ds_read2_b32 v[12:13], v56 offset0:33 offset1:41
	ds_read2_b32 v[14:15], v56 offset1:8
	ds_read2_b32 v[16:17], v56 offset0:66 offset1:74
	ds_read2_b32 v[18:19], v56 offset0:99 offset1:107
	ds_read2_b32 v[20:21], v56 offset0:132 offset1:140
	ds_read2_b32 v[22:23], v56 offset0:165 offset1:173
	ds_read2_b32 v[24:25], v56 offset0:198 offset1:206
	ds_read2_b32 v[26:27], v56 offset0:231 offset1:239
	s_add_i32 s12, s20, s29
	v_or_b32_e32 v28, s12, v55
	v_ashrrev_i32_e32 v29, 31, v28
	v_lshl_add_u64 v[10:11], s[18:19], 1, v[4:5]
	v_lshlrev_b64 v[28:29], 11, v[28:29]
	s_waitcnt lgkmcnt(6)
	v_cvt_pk_bf16_f32 v6, v14, v12
	s_waitcnt lgkmcnt(4)
	v_cvt_pk_bf16_f32 v7, v16, v18
	s_waitcnt lgkmcnt(2)
	v_cvt_pk_bf16_f32 v8, v20, v22
	s_waitcnt lgkmcnt(0)
	v_cvt_pk_bf16_f32 v9, v24, v26
	v_lshl_add_u64 v[28:29], v[10:11], 0, v[28:29]
	v_or_b32_e32 v12, s12, v57
	global_store_dwordx4 v[28:29], v[6:9], off sc1
	v_or_b32_e32 v28, s12, v58
	v_ashrrev_i32_e32 v29, 31, v28
	v_cvt_pk_bf16_f32 v6, v15, v13
	v_ashrrev_i32_e32 v13, 31, v12
	v_lshlrev_b64 v[12:13], 11, v[12:13]
	v_cvt_pk_bf16_f32 v7, v17, v19
	v_cvt_pk_bf16_f32 v8, v21, v23
	v_cvt_pk_bf16_f32 v9, v25, v27
	v_lshl_add_u64 v[12:13], v[10:11], 0, v[12:13]
	global_store_dwordx4 v[12:13], v[6:9], off sc1
	ds_read2_b32 v[12:13], v56 offset0:49 offset1:57
	ds_read2_b32 v[14:15], v56 offset0:16 offset1:24
	ds_read2_b32 v[16:17], v56 offset0:82 offset1:90
	ds_read2_b32 v[18:19], v56 offset0:115 offset1:123
	ds_read2_b32 v[20:21], v56 offset0:148 offset1:156
	ds_read2_b32 v[22:23], v56 offset0:181 offset1:189
	ds_read2_b32 v[24:25], v56 offset0:214 offset1:222
	ds_read2_b32 v[26:27], v56 offset0:247 offset1:255
	v_lshlrev_b64 v[28:29], 11, v[28:29]
	s_waitcnt lgkmcnt(6)
	v_cvt_pk_bf16_f32 v6, v14, v12
	s_waitcnt lgkmcnt(4)
	v_cvt_pk_bf16_f32 v7, v16, v18
	s_waitcnt lgkmcnt(2)
	v_cvt_pk_bf16_f32 v8, v20, v22
	s_waitcnt lgkmcnt(0)
	v_cvt_pk_bf16_f32 v9, v24, v26
	v_lshl_add_u64 v[28:29], v[10:11], 0, v[28:29]
	v_or_b32_e32 v12, s12, v59
	global_store_dwordx4 v[28:29], v[6:9], off sc1
	s_nop 1
	v_cvt_pk_bf16_f32 v6, v15, v13
	v_ashrrev_i32_e32 v13, 31, v12
	v_lshlrev_b64 v[12:13], 11, v[12:13]
	v_cvt_pk_bf16_f32 v7, v17, v19
	v_cvt_pk_bf16_f32 v8, v21, v23
	v_cvt_pk_bf16_f32 v9, v25, v27
	v_lshl_add_u64 v[10:11], v[10:11], 0, v[12:13]
	global_store_dwordx4 v[10:11], v[6:9], off sc1
	s_waitcnt lgkmcnt(0)
	s_cbranch_execnz .LBB0_1253
	s_branch .LBB0_1338
